# combination: all GEMM K-loop restructures + RoPE epilogue + diff-attention QK/PV LDS read pipelining
# speedup vs baseline: 1.0078x; 1.0078x over previous
; DI unsigned pack2(float a, float b) { bf2_t v = __builtin_convertvector((f32x2){a, b}, bf2_t); return __builtin_bit_cast(unsigned, v); }
; #define MFMA(a, b, c) __builtin_amdgcn_mfma_f32_32x32x16_bf16((a), (b), (c), 0, 0, 0)
; template <int NDT> DI void pv_tile(const bf16_t* sV, const f32x16 (&P)[2], f32x16 (&O)[NDT], int r, int h) {
; #pragma unroll
;   for (int mt = 0; mt < 2; ++mt)
; #pragma unroll
;     for (int sp = 0; sp < 2; ++sp) {
;       u32x4 pk;
;       pk.x = pack2(P[mt][8 * sp + 0], P[mt][8 * sp + 1]); pk.y = pack2(P[mt][8 * sp + 2], P[mt][8 * sp + 3]);
;       pk.z = pack2(P[mt][8 * sp + 4], P[mt][8 * sp + 5]); pk.w = pack2(P[mt][8 * sp + 6], P[mt][8 * sp + 7]);
;       const bf16x8 pb = __builtin_bit_cast(bf16x8, pk);
; #pragma unroll
;       for (int dt = 0; dt < NDT; ++dt) {
;         const bf16_t* vp = sV + (dt * 32 + r) * 68 + mt * 32 + sp * 16 + 4 * h;
;         const bf16x4 lo = *(const bf16x4*)vp, hi = *(const bf16x4*)(vp + 8);
;         const bf16x8 va = __builtin_shufflevector(lo, hi, 0, 1, 2, 3, 4, 5, 6, 7);
;         O[dt] = MFMA(va, pb, O[dt]);
;       }
;       if (NDT > 2) __builtin_amdgcn_sched_barrier(0);
;     }
; }
; template <int NDT> DI void scale_o(f32x16 (&O)[NDT], float a) {
; #pragma unroll
;   for (int dt = 0; dt < NDT; ++dt)
; #pragma unroll
;     for (int i = 0; i < 16; ++i) O[dt][i] *= a;
; }
.LBB0_756:
	s_or_b64 exec, exec, s[82:83]
	s_nop 5
	v_add_u32_e32 v98, v246, v247
	v_add_u32_e32 v99, 0x2000, v98
	v_add_u32_e32 v100, 0x3000, v98
	v_add_u32_e32 v101, 0x4000, v98
	v_add_u32_e32 v98, 0x5000, v98
	v_cvt_pk_bf16_f32 v0, v0, v1
	v_cvt_pk_bf16_f32 v1, v2, v3
	v_cvt_pk_bf16_f32 v2, v4, v5
	v_cvt_pk_bf16_f32 v3, v6, v7
	ds_read2_b64 v[4:7], v99 offset0:128 offset1:130
	v_cvt_pk_bf16_f32 v8, v8, v9
	v_cvt_pk_bf16_f32 v9, v10, v11
	v_cvt_pk_bf16_f32 v10, v12, v13
	v_cvt_pk_bf16_f32 v11, v14, v15
	ds_read2_b64 v[12:15], v100 offset0:160 offset1:162
	v_cvt_pk_bf16_f32 v16, v16, v17
	v_cvt_pk_bf16_f32 v17, v18, v19
	v_cvt_pk_bf16_f32 v18, v20, v21
	v_cvt_pk_bf16_f32 v19, v22, v23
	ds_read2_b64 v[20:23], v101 offset0:192 offset1:194
	v_cvt_pk_bf16_f32 v24, v24, v25
	v_cvt_pk_bf16_f32 v25, v26, v27
	v_cvt_pk_bf16_f32 v26, v28, v29
	v_cvt_pk_bf16_f32 v27, v30, v31
	ds_read2_b64 v[28:31], v98 offset0:224 offset1:226
	v_pk_mul_f32 v[96:97], v[96:97], v[202:203] op_sel_hi:[1,0]
	v_pk_mul_f32 v[94:95], v[94:95], v[202:203] op_sel_hi:[1,0]
	v_pk_mul_f32 v[92:93], v[92:93], v[202:203] op_sel_hi:[1,0]
	v_pk_mul_f32 v[90:91], v[90:91], v[202:203] op_sel_hi:[1,0]
	v_pk_mul_f32 v[88:89], v[88:89], v[202:203] op_sel_hi:[1,0]
	v_pk_mul_f32 v[86:87], v[86:87], v[202:203] op_sel_hi:[1,0]
	v_pk_mul_f32 v[84:85], v[84:85], v[202:203] op_sel_hi:[1,0]
	v_pk_mul_f32 v[82:83], v[82:83], v[202:203] op_sel_hi:[1,0]
	s_waitcnt lgkmcnt(3)
	s_nop 0
	v_mfma_f32_32x32x16_bf16 v[82:97], v[4:7], v[0:3], v[82:97]
	ds_read2_b64 v[4:7], v99 offset0:132 offset1:134
	v_pk_mul_f32 v[80:81], v[80:81], v[202:203] op_sel_hi:[1,0]
	v_mul_f32_e64 v78, v78, v202
	v_mul_f32_e64 v79, v79, v202
	v_mul_f32_e64 v76, v76, v202
	v_mul_f32_e64 v77, v77, v202
	v_pk_mul_f32 v[74:75], v[74:75], v[202:203] op_sel_hi:[1,0]
	v_pk_mul_f32 v[72:73], v[72:73], v[202:203] op_sel_hi:[1,0]
	v_pk_mul_f32 v[70:71], v[70:71], v[202:203] op_sel_hi:[1,0]
	v_pk_mul_f32 v[68:69], v[68:69], v[202:203] op_sel_hi:[1,0]
	v_pk_mul_f32 v[66:67], v[66:67], v[202:203] op_sel_hi:[1,0]
	s_waitcnt lgkmcnt(3)
	s_nop 0
	v_mfma_f32_32x32x16_bf16 v[66:81], v[12:15], v[0:3], v[66:81]
	ds_read2_b64 v[12:15], v100 offset0:164 offset1:166
	v_pk_mul_f32 v[64:65], v[64:65], v[202:203] op_sel_hi:[1,0]
	v_mul_f32_e64 v62, v62, v202
	v_mul_f32_e64 v63, v63, v202
	v_mul_f32_e64 v60, v60, v202
	v_mul_f32_e64 v61, v61, v202
	v_pk_mul_f32 v[58:59], v[58:59], v[202:203] op_sel_hi:[1,0]
	v_pk_mul_f32 v[56:57], v[56:57], v[202:203] op_sel_hi:[1,0]
	v_pk_mul_f32 v[54:55], v[54:55], v[202:203] op_sel_hi:[1,0]
	v_pk_mul_f32 v[52:53], v[52:53], v[202:203] op_sel_hi:[1,0]
	v_pk_mul_f32 v[50:51], v[50:51], v[202:203] op_sel_hi:[1,0]
	s_waitcnt lgkmcnt(3)
	s_nop 0
	v_mfma_f32_32x32x16_bf16 v[50:65], v[20:23], v[0:3], v[50:65]
	ds_read2_b64 v[20:23], v101 offset0:196 offset1:198
	v_pk_mul_f32 v[48:49], v[48:49], v[202:203] op_sel_hi:[1,0]
	v_mul_f32_e64 v46, v46, v202
	v_mul_f32_e64 v47, v47, v202
	v_mul_f32_e64 v44, v44, v202
	v_mul_f32_e64 v45, v45, v202
	v_pk_mul_f32 v[42:43], v[42:43], v[202:203] op_sel_hi:[1,0]
	v_pk_mul_f32 v[40:41], v[40:41], v[202:203] op_sel_hi:[1,0]
	v_pk_mul_f32 v[38:39], v[38:39], v[202:203] op_sel_hi:[1,0]
	v_pk_mul_f32 v[36:37], v[36:37], v[202:203] op_sel_hi:[1,0]
	v_pk_mul_f32 v[34:35], v[34:35], v[202:203] op_sel_hi:[1,0]
	s_waitcnt lgkmcnt(3)
	s_nop 0
	v_mfma_f32_32x32x16_bf16 v[34:49], v[28:31], v[0:3], v[34:49]
	ds_read2_b64 v[28:31], v98 offset0:228 offset1:230
	s_waitcnt lgkmcnt(3)
	v_mfma_f32_32x32x16_bf16 v[82:97], v[4:7], v[8:11], v[82:97]
	ds_read2_b64 v[4:7], v99 offset0:136 offset1:138
	s_waitcnt lgkmcnt(3)
	v_mfma_f32_32x32x16_bf16 v[66:81], v[12:15], v[8:11], v[66:81]
	ds_read2_b64 v[12:15], v100 offset0:168 offset1:170
	s_waitcnt lgkmcnt(3)
	v_mfma_f32_32x32x16_bf16 v[50:65], v[20:23], v[8:11], v[50:65]
	ds_read2_b64 v[20:23], v101 offset0:200 offset1:202
	s_waitcnt lgkmcnt(3)
	v_mfma_f32_32x32x16_bf16 v[34:49], v[28:31], v[8:11], v[34:49]
	ds_read2_b64 v[28:31], v98 offset0:232 offset1:234
	s_waitcnt lgkmcnt(3)
	v_mfma_f32_32x32x16_bf16 v[82:97], v[4:7], v[16:19], v[82:97]
	ds_read2_b64 v[4:7], v99 offset0:140 offset1:142
	s_waitcnt lgkmcnt(3)
	v_mfma_f32_32x32x16_bf16 v[66:81], v[12:15], v[16:19], v[66:81]
	ds_read2_b64 v[12:15], v100 offset0:172 offset1:174
	s_waitcnt lgkmcnt(3)
	v_mfma_f32_32x32x16_bf16 v[50:65], v[20:23], v[16:19], v[50:65]
	ds_read2_b64 v[20:23], v101 offset0:204 offset1:206
	s_waitcnt lgkmcnt(3)
	v_mfma_f32_32x32x16_bf16 v[34:49], v[28:31], v[16:19], v[34:49]
	ds_read2_b64 v[28:31], v98 offset0:236 offset1:238
	s_waitcnt lgkmcnt(3)
	v_mfma_f32_32x32x16_bf16 v[82:97], v[4:7], v[24:27], v[82:97]
	s_waitcnt lgkmcnt(2)
	v_mfma_f32_32x32x16_bf16 v[66:81], v[12:15], v[24:27], v[66:81]
	s_waitcnt lgkmcnt(1)
	v_mfma_f32_32x32x16_bf16 v[50:65], v[20:23], v[24:27], v[50:65]
	s_waitcnt lgkmcnt(0)
	v_mfma_f32_32x32x16_bf16 v[34:49], v[28:31], v[24:27], v[34:49]

; #define MFMA(a, b, c) __builtin_amdgcn_mfma_f32_32x32x16_bf16((a), (b), (c), 0, 0, 0)
; DI float shx32(float v) { return __shfl_xor(v, 32); }
; DI void qk_tile(const bf16_t* sK, const bf16x8 (&qf)[4], f32x16 (&Sx)[2], int r, int h) {
; #pragma unroll
;   for (int mt = 0; mt < 2; ++mt) {
;     f32x16 a;
; #pragma unroll
;     for (int i = 0; i < 16; ++i) a[i] = 0.f;
; #pragma unroll
;     for (int s = 0; s < 4; ++s) {
;       const bf16x8 k = *(const bf16x8*)(sK + (mt * 32 + r) * 72 + s * 16 + h * 8);
;       a = MFMA(k, qf[s], a);
;     }
;     Sx[mt] = a;
;   }
; }
; template <bool MASKED>
; DI float online_softmax_t(f32x16 (&Sx)[2], unsigned vb, float& m, float& l) {
;   float mx = NEG;
; #pragma unroll
;   for (int mt = 0; mt < 2; ++mt)
; #pragma unroll
;     for (int i = 0; i < 16; ++i) {
;       float s = Sx[mt][i];
;       if (MASKED) { s = ((vb >> (mt * 16 + i)) & 1u) ? s : NEG; Sx[mt][i] = s; }
;       mx = fmaxf(mx, s);
;     }
;   mx = fmaxf(mx, shx32(mx));
;   const float mn = fmaxf(m, mx);
;   const float alpha = __builtin_amdgcn_exp2f((m - mn) * L2E);
;   const float mb = mn * L2E;
;   f32x2 sum2 = {0.f, 0.f};
;   const f32x2 l2e2 = {L2E, L2E}, mb2 = {mb, mb};
; #pragma unroll
;   for (int mt = 0; mt < 2; ++mt)
; #pragma unroll
;     for (int i = 0; i < 16; i += 2) {
;       const f32x2 t = (f32x2){Sx[mt][i], Sx[mt][i + 1]} * l2e2 - mb2;
;       f32x2 p = {__builtin_amdgcn_exp2f(t.x), __builtin_amdgcn_exp2f(t.y)};
;       if (MASKED) { p.x = ((vb >> (mt * 16 + i)) & 1u) ? p.x : 0.f; p.y = ((vb >> (mt * 16 + i + 1)) & 1u) ? p.y : 0.f; }
;       Sx[mt][i] = p.x; Sx[mt][i + 1] = p.y;
;       sum2 += p;
;     }
;   l = l * alpha + (sum2.x + sum2.y);
;   m = mn;
;   return alpha;
; }
.LBB0_760:
	v_cmp_le_i32_e32 vcc, s91, v245
	s_and_saveexec_b64 s[78:79], vcc
	s_cbranch_execz .LBB0_757
	ds_read_b128 v[0:3], v249
	ds_read_b128 v[4:7], v249 offset:32
	ds_read_b128 v[8:11], v249 offset:64
	ds_read_b128 v[12:15], v249 offset:96
	ds_read_b128 v[16:19], v249 offset:4608
	ds_read_b128 v[20:23], v249 offset:4640
	ds_read_b128 v[24:27], v249 offset:4672
	ds_read_b128 v[28:31], v249 offset:4704
	s_add_i32 s0, s80, -1
	v_cmp_le_i32_e32 vcc, s0, v244
	s_waitcnt lgkmcnt(7)
	v_mfma_f32_32x32x16_bf16 v[114:129], v[0:3], v[130:133], 0
	s_waitcnt lgkmcnt(6)
	v_mfma_f32_32x32x16_bf16 v[114:129], v[4:7], v[134:137], v[114:129]
	s_waitcnt lgkmcnt(5)
	v_mfma_f32_32x32x16_bf16 v[114:129], v[8:11], v[138:141], v[114:129]
	s_waitcnt lgkmcnt(4)
	v_mfma_f32_32x32x16_bf16 v[114:129], v[12:15], v[142:145], v[114:129]
	s_waitcnt lgkmcnt(3)
	v_mfma_f32_32x32x16_bf16 v[98:113], v[16:19], v[130:133], 0
	s_waitcnt lgkmcnt(2)
	v_mfma_f32_32x32x16_bf16 v[98:113], v[20:23], v[134:137], v[98:113]
	s_waitcnt lgkmcnt(1)
	v_mfma_f32_32x32x16_bf16 v[98:113], v[24:27], v[138:141], v[98:113]
	s_waitcnt lgkmcnt(0)
	v_mfma_f32_32x32x16_bf16 v[98:113], v[28:31], v[142:145], v[98:113]
	s_and_saveexec_b64 s[0:1], vcc
	s_xor_b64 s[0:1], exec, s[0:1]
	s_cbranch_execz .LBB0_763
	v_max3_f32 v0, v114, s67, v115
	v_max3_f32 v0, v0, v116, v117
	v_max3_f32 v0, v0, v118, v119
	v_max3_f32 v0, v0, v120, v121
	v_max3_f32 v0, v0, v122, v123
	v_max3_f32 v0, v0, v124, v125
	v_max3_f32 v0, v0, v126, v127
	v_max3_f32 v0, v0, v128, v129
	s_nop 0
	v_max3_f32 v0, v0, v98, v99
	v_max3_f32 v0, v0, v100, v101
	v_max3_f32 v0, v0, v102, v103
	v_max3_f32 v0, v0, v104, v105
	v_and_b32_e32 v2, 64, v208
	v_max3_f32 v0, v0, v106, v107
	v_xor_b32_e32 v1, 32, v208
	v_add_u32_e32 v2, 64, v2
	v_max3_f32 v0, v0, v108, v109
	v_cmp_lt_i32_e32 vcc, v1, v2
	v_max3_f32 v0, v0, v110, v111
	v_max3_f32 v0, v0, v112, v113
	v_cndmask_b32_e32 v1, v208, v1, vcc
	v_lshlrev_b32_e32 v1, 2, v1
	ds_bpermute_b32 v1, v1, v0
	s_mov_b32 s2, 0x3fb8aa3b
	s_waitcnt lgkmcnt(0)
	v_max3_f32 v203, v205, v0, v1
	v_mul_f32_e32 v30, 0x3fb8aa3b, v203
	v_pk_fma_f32 v[0:1], v[114:115], s[2:3], v[30:31] op_sel_hi:[1,0,0] neg_lo:[0,0,1] neg_hi:[0,0,1]
	v_pk_fma_f32 v[2:3], v[116:117], s[2:3], v[30:31] op_sel_hi:[1,0,0] neg_lo:[0,0,1] neg_hi:[0,0,1]
	v_exp_f32_e32 v0, v0
	v_exp_f32_e32 v1, v1
	v_exp_f32_e32 v2, v2
	v_exp_f32_e32 v3, v3
	v_pk_fma_f32 v[6:7], v[120:121], s[2:3], v[30:31] op_sel_hi:[1,0,0] neg_lo:[0,0,1] neg_hi:[0,0,1]
	v_pk_add_f32 v[4:5], v[0:1], 0 op_sel_hi:[1,0]
	v_exp_f32_e32 v6, v6
	v_pk_add_f32 v[12:13], v[2:3], v[4:5]
	v_pk_fma_f32 v[4:5], v[118:119], s[2:3], v[30:31] op_sel_hi:[1,0,0] neg_lo:[0,0,1] neg_hi:[0,0,1]
	v_exp_f32_e32 v7, v7
	v_exp_f32_e32 v4, v4
	v_exp_f32_e32 v5, v5
	v_pk_fma_f32 v[8:9], v[122:123], s[2:3], v[30:31] op_sel_hi:[1,0,0] neg_lo:[0,0,1] neg_hi:[0,0,1]
	v_pk_fma_f32 v[10:11], v[124:125], s[2:3], v[30:31] op_sel_hi:[1,0,0] neg_lo:[0,0,1] neg_hi:[0,0,1]
	v_exp_f32_e32 v8, v8
	v_exp_f32_e32 v9, v9
	v_exp_f32_e32 v10, v10
	v_exp_f32_e32 v11, v11
	v_pk_add_f32 v[12:13], v[4:5], v[12:13]
	v_pk_fma_f32 v[14:15], v[128:129], s[2:3], v[30:31] op_sel_hi:[1,0,0] neg_lo:[0,0,1] neg_hi:[0,0,1]
	v_pk_add_f32 v[12:13], v[6:7], v[12:13]
	v_exp_f32_e32 v14, v14
	v_pk_add_f32 v[12:13], v[8:9], v[12:13]
	v_exp_f32_e32 v15, v15
	v_pk_add_f32 v[20:21], v[10:11], v[12:13]
	v_pk_fma_f32 v[12:13], v[126:127], s[2:3], v[30:31] op_sel_hi:[1,0,0] neg_lo:[0,0,1] neg_hi:[0,0,1]
	v_pk_fma_f32 v[16:17], v[98:99], s[2:3], v[30:31] op_sel_hi:[1,0,0] neg_lo:[0,0,1] neg_hi:[0,0,1]
	v_exp_f32_e32 v12, v12
	v_exp_f32_e32 v13, v13
	v_exp_f32_e32 v16, v16
	v_exp_f32_e32 v17, v17
	v_pk_fma_f32 v[18:19], v[100:101], s[2:3], v[30:31] op_sel_hi:[1,0,0] neg_lo:[0,0,1] neg_hi:[0,0,1]
	v_pk_add_f32 v[20:21], v[12:13], v[20:21]
	v_exp_f32_e32 v18, v18
	v_exp_f32_e32 v19, v19
	v_pk_add_f32 v[20:21], v[14:15], v[20:21]
	v_pk_fma_f32 v[22:23], v[104:105], s[2:3], v[30:31] op_sel_hi:[1,0,0] neg_lo:[0,0,1] neg_hi:[0,0,1]
	v_pk_add_f32 v[20:21], v[16:17], v[20:21]
	v_exp_f32_e32 v22, v22
	v_pk_add_f32 v[28:29], v[18:19], v[20:21]
	v_pk_fma_f32 v[20:21], v[102:103], s[2:3], v[30:31] op_sel_hi:[1,0,0] neg_lo:[0,0,1] neg_hi:[0,0,1]
	v_exp_f32_e32 v23, v23
	v_exp_f32_e32 v20, v20
	v_exp_f32_e32 v21, v21
	v_pk_fma_f32 v[24:25], v[106:107], s[2:3], v[30:31] op_sel_hi:[1,0,0] neg_lo:[0,0,1] neg_hi:[0,0,1]
	v_pk_fma_f32 v[26:27], v[108:109], s[2:3], v[30:31] op_sel_hi:[1,0,0] neg_lo:[0,0,1] neg_hi:[0,0,1]
	v_exp_f32_e32 v24, v24
	v_exp_f32_e32 v25, v25
	v_exp_f32_e32 v26, v26
	v_exp_f32_e32 v27, v27
	v_pk_add_f32 v[28:29], v[20:21], v[28:29]
	v_sub_f32_e32 v100, v205, v203
	v_pk_add_f32 v[28:29], v[22:23], v[28:29]
	v_mul_f32_e32 v100, 0x3fb8aa3b, v100
	v_pk_add_f32 v[28:29], v[24:25], v[28:29]
	v_exp_f32_e32 v202, v100
	v_pk_add_f32 v[98:99], v[26:27], v[28:29]
	v_pk_fma_f32 v[28:29], v[110:111], s[2:3], v[30:31] op_sel_hi:[1,0,0] neg_lo:[0,0,1] neg_hi:[0,0,1]
	v_pk_fma_f32 v[30:31], v[112:113], s[2:3], v[30:31] op_sel_hi:[1,0,0] neg_lo:[0,0,1] neg_hi:[0,0,1]
	v_exp_f32_e32 v28, v28
	v_exp_f32_e32 v29, v29
	v_exp_f32_e32 v30, v30
	v_exp_f32_e32 v31, v31
	v_pk_add_f32 v[98:99], v[28:29], v[98:99]
	s_nop 0
	v_pk_add_f32 v[98:99], v[30:31], v[98:99]
	s_nop 0
	v_add_f32_e32 v98, v98, v99
	v_fmac_f32_e32 v98, v179, v202
	v_mov_b32_e32 v179, v98
	v_mov_b32_e32 v205, v203

; DI unsigned pack2(float a, float b) { bf2_t v = __builtin_convertvector((f32x2){a, b}, bf2_t); return __builtin_bit_cast(unsigned, v); }
; #define MFMA(a, b, c) __builtin_amdgcn_mfma_f32_32x32x16_bf16((a), (b), (c), 0, 0, 0)
; template <int NDT> DI void pv_tile(const bf16_t* sV, const f32x16 (&P)[2], f32x16 (&O)[NDT], int r, int h) {
; #pragma unroll
;   for (int mt = 0; mt < 2; ++mt)
; #pragma unroll
;     for (int sp = 0; sp < 2; ++sp) {
;       u32x4 pk;
;       pk.x = pack2(P[mt][8 * sp + 0], P[mt][8 * sp + 1]); pk.y = pack2(P[mt][8 * sp + 2], P[mt][8 * sp + 3]);
;       pk.z = pack2(P[mt][8 * sp + 4], P[mt][8 * sp + 5]); pk.w = pack2(P[mt][8 * sp + 6], P[mt][8 * sp + 7]);
;       const bf16x8 pb = __builtin_bit_cast(bf16x8, pk);
; #pragma unroll
;       for (int dt = 0; dt < NDT; ++dt) {
;         const bf16_t* vp = sV + (dt * 32 + r) * 68 + mt * 32 + sp * 16 + 4 * h;
;         const bf16x4 lo = *(const bf16x4*)vp, hi = *(const bf16x4*)(vp + 8);
;         const bf16x8 va = __builtin_shufflevector(lo, hi, 0, 1, 2, 3, 4, 5, 6, 7);
;         O[dt] = MFMA(va, pb, O[dt]);
;       }
;       if (NDT > 2) __builtin_amdgcn_sched_barrier(0);
;     }
; }
; template <int NDT> DI void scale_o(f32x16 (&O)[NDT], float a) {
; #pragma unroll
;   for (int dt = 0; dt < NDT; ++dt)
; #pragma unroll
;     for (int i = 0; i < 16; ++i) O[dt][i] *= a;
; }
.LBB0_766:
	s_or_b64 exec, exec, s[76:77]
	v_pk_mul_f32 v[110:111], v[110:111], v[32:33] op_sel_hi:[1,0]
	v_pk_mul_f32 v[108:109], v[108:109], v[32:33] op_sel_hi:[1,0]
	v_pk_mul_f32 v[106:107], v[106:107], v[32:33] op_sel_hi:[1,0]
	v_pk_mul_f32 v[104:105], v[104:105], v[32:33] op_sel_hi:[1,0]
	v_pk_mul_f32 v[102:103], v[102:103], v[32:33] op_sel_hi:[1,0]
	v_pk_mul_f32 v[100:101], v[100:101], v[32:33] op_sel_hi:[1,0]
	v_pk_mul_f32 v[98:99], v[98:99], v[32:33] op_sel_hi:[1,0]
	v_pk_mul_f32 v[96:97], v[96:97], v[32:33] op_sel_hi:[1,0]
	v_pk_mul_f32 v[94:95], v[94:95], v[32:33] op_sel_hi:[1,0]
	v_pk_mul_f32 v[92:93], v[92:93], v[32:33] op_sel_hi:[1,0]
	v_pk_mul_f32 v[90:91], v[90:91], v[32:33] op_sel_hi:[1,0]
	v_pk_mul_f32 v[88:89], v[88:89], v[32:33] op_sel_hi:[1,0]
	v_pk_mul_f32 v[86:87], v[86:87], v[32:33] op_sel_hi:[1,0]
	v_pk_mul_f32 v[84:85], v[84:85], v[32:33] op_sel_hi:[1,0]
	v_pk_mul_f32 v[82:83], v[82:83], v[32:33] op_sel_hi:[1,0]
	v_pk_mul_f32 v[80:81], v[80:81], v[32:33] op_sel_hi:[1,0]
	v_pk_mul_f32 v[78:79], v[78:79], v[32:33] op_sel_hi:[1,0]
	v_pk_mul_f32 v[76:77], v[76:77], v[32:33] op_sel_hi:[1,0]
	v_pk_mul_f32 v[74:75], v[74:75], v[32:33] op_sel_hi:[1,0]
	v_pk_mul_f32 v[72:73], v[72:73], v[32:33] op_sel_hi:[1,0]
	v_pk_mul_f32 v[70:71], v[70:71], v[32:33] op_sel_hi:[1,0]
	v_pk_mul_f32 v[68:69], v[68:69], v[32:33] op_sel_hi:[1,0]
	v_pk_mul_f32 v[66:67], v[66:67], v[32:33] op_sel_hi:[1,0]
	v_pk_mul_f32 v[64:65], v[64:65], v[32:33] op_sel_hi:[1,0]
	v_pk_mul_f32 v[62:63], v[62:63], v[32:33] op_sel_hi:[1,0]
	v_pk_mul_f32 v[60:61], v[60:61], v[32:33] op_sel_hi:[1,0]
	v_pk_mul_f32 v[58:59], v[58:59], v[32:33] op_sel_hi:[1,0]
	v_pk_mul_f32 v[56:57], v[56:57], v[32:33] op_sel_hi:[1,0]
	v_pk_mul_f32 v[54:55], v[54:55], v[32:33] op_sel_hi:[1,0]
	v_pk_mul_f32 v[52:53], v[52:53], v[32:33] op_sel_hi:[1,0]
	v_pk_mul_f32 v[50:51], v[50:51], v[32:33] op_sel_hi:[1,0]
	v_pk_mul_f32 v[48:49], v[48:49], v[32:33] op_sel_hi:[1,0]
	v_add_u32_e32 v32, v246, v247
	v_add_u32_e32 v34, 0x2000, v32
	v_add_u32_e32 v35, 0x3000, v32
	v_add_u32_e32 v36, 0x4000, v32
	v_add_u32_e32 v32, 0x5000, v32
	v_cvt_pk_bf16_f32 v0, v0, v1
	v_cvt_pk_bf16_f32 v1, v2, v3
	v_cvt_pk_bf16_f32 v2, v4, v5
	v_cvt_pk_bf16_f32 v3, v6, v7
	ds_read2_b64 v[4:7], v34 offset0:128 offset1:130
	v_cvt_pk_bf16_f32 v8, v8, v9
	v_cvt_pk_bf16_f32 v9, v10, v11
	v_cvt_pk_bf16_f32 v10, v12, v13
	v_cvt_pk_bf16_f32 v11, v14, v15
	ds_read2_b64 v[12:15], v35 offset0:160 offset1:162
	v_cvt_pk_bf16_f32 v16, v16, v17
	v_cvt_pk_bf16_f32 v17, v18, v19
	v_cvt_pk_bf16_f32 v18, v20, v21
	v_cvt_pk_bf16_f32 v19, v22, v23
	ds_read2_b64 v[20:23], v36 offset0:192 offset1:194
	v_cvt_pk_bf16_f32 v24, v24, v25
	v_cvt_pk_bf16_f32 v25, v26, v27
	v_cvt_pk_bf16_f32 v26, v28, v29
	v_cvt_pk_bf16_f32 v27, v30, v31
	ds_read2_b64 v[28:31], v32 offset0:224 offset1:226
	s_waitcnt lgkmcnt(3)
	v_mfma_f32_32x32x16_bf16 v[96:111], v[4:7], v[0:3], v[96:111]
	ds_read2_b64 v[4:7], v34 offset0:132 offset1:134
	s_waitcnt lgkmcnt(3)
	v_mfma_f32_32x32x16_bf16 v[80:95], v[12:15], v[0:3], v[80:95]
	ds_read2_b64 v[12:15], v35 offset0:164 offset1:166
	s_waitcnt lgkmcnt(3)
	v_mfma_f32_32x32x16_bf16 v[64:79], v[20:23], v[0:3], v[64:79]
	ds_read2_b64 v[20:23], v36 offset0:196 offset1:198
	s_waitcnt lgkmcnt(3)
	v_mfma_f32_32x32x16_bf16 v[48:63], v[28:31], v[0:3], v[48:63]
	ds_read2_b64 v[28:31], v32 offset0:228 offset1:230
	s_waitcnt lgkmcnt(3)
	v_mfma_f32_32x32x16_bf16 v[96:111], v[4:7], v[8:11], v[96:111]
	ds_read2_b64 v[4:7], v34 offset0:136 offset1:138
	s_waitcnt lgkmcnt(3)
	v_mfma_f32_32x32x16_bf16 v[80:95], v[12:15], v[8:11], v[80:95]
	ds_read2_b64 v[12:15], v35 offset0:168 offset1:170
	s_waitcnt lgkmcnt(3)
	v_mfma_f32_32x32x16_bf16 v[64:79], v[20:23], v[8:11], v[64:79]
	ds_read2_b64 v[20:23], v36 offset0:200 offset1:202
	s_waitcnt lgkmcnt(3)
	v_mfma_f32_32x32x16_bf16 v[48:63], v[28:31], v[8:11], v[48:63]
	ds_read2_b64 v[28:31], v32 offset0:232 offset1:234
	s_waitcnt lgkmcnt(3)
	v_mfma_f32_32x32x16_bf16 v[96:111], v[4:7], v[16:19], v[96:111]
	ds_read2_b64 v[4:7], v34 offset0:140 offset1:142
	s_waitcnt lgkmcnt(3)
	v_mfma_f32_32x32x16_bf16 v[80:95], v[12:15], v[16:19], v[80:95]
	ds_read2_b64 v[12:15], v35 offset0:172 offset1:174
	s_waitcnt lgkmcnt(3)
	v_mfma_f32_32x32x16_bf16 v[64:79], v[20:23], v[16:19], v[64:79]
	ds_read2_b64 v[20:23], v36 offset0:204 offset1:206
	s_waitcnt lgkmcnt(3)
	v_mfma_f32_32x32x16_bf16 v[48:63], v[28:31], v[16:19], v[48:63]
	ds_read2_b64 v[28:31], v32 offset0:236 offset1:238
	s_waitcnt lgkmcnt(3)
	v_mfma_f32_32x32x16_bf16 v[96:111], v[4:7], v[24:27], v[96:111]
	s_waitcnt lgkmcnt(2)
	v_mfma_f32_32x32x16_bf16 v[80:95], v[12:15], v[24:27], v[80:95]
	s_waitcnt lgkmcnt(1)
	v_mfma_f32_32x32x16_bf16 v[64:79], v[20:23], v[24:27], v[64:79]
	s_waitcnt lgkmcnt(0)
	v_mfma_f32_32x32x16_bf16 v[48:63], v[28:31], v[24:27], v[48:63]

; #define MFMA(a, b, c) __builtin_amdgcn_mfma_f32_32x32x16_bf16((a), (b), (c), 0, 0, 0)
; DI float shx32(float v) { return __shfl_xor(v, 32); }
; DI void qk_tile(const bf16_t* sK, const bf16x8 (&qf)[4], f32x16 (&Sx)[2], int r, int h) {
; #pragma unroll
;   for (int mt = 0; mt < 2; ++mt) {
;     f32x16 a;
; #pragma unroll
;     for (int i = 0; i < 16; ++i) a[i] = 0.f;
; #pragma unroll
;     for (int s = 0; s < 4; ++s) {
;       const bf16x8 k = *(const bf16x8*)(sK + (mt * 32 + r) * 72 + s * 16 + h * 8);
;       a = MFMA(k, qf[s], a);
;     }
;     Sx[mt] = a;
;   }
; }
; template <bool MASKED>
; DI float online_softmax_t(f32x16 (&Sx)[2], unsigned vb, float& m, float& l) {
;   float mx = NEG;
; #pragma unroll
;   for (int mt = 0; mt < 2; ++mt)
; #pragma unroll
;     for (int i = 0; i < 16; ++i) {
;       float s = Sx[mt][i];
;       if (MASKED) { s = ((vb >> (mt * 16 + i)) & 1u) ? s : NEG; Sx[mt][i] = s; }
;       mx = fmaxf(mx, s);
;     }
;   mx = fmaxf(mx, shx32(mx));
;   const float mn = fmaxf(m, mx);
;   const float alpha = __builtin_amdgcn_exp2f((m - mn) * L2E);
;   const float mb = mn * L2E;
;   f32x2 sum2 = {0.f, 0.f};
;   const f32x2 l2e2 = {L2E, L2E}, mb2 = {mb, mb};
; #pragma unroll
;   for (int mt = 0; mt < 2; ++mt)
; #pragma unroll
;     for (int i = 0; i < 16; i += 2) {
;       const f32x2 t = (f32x2){Sx[mt][i], Sx[mt][i + 1]} * l2e2 - mb2;
;       f32x2 p = {__builtin_amdgcn_exp2f(t.x), __builtin_amdgcn_exp2f(t.y)};
;       if (MASKED) { p.x = ((vb >> (mt * 16 + i)) & 1u) ? p.x : 0.f; p.y = ((vb >> (mt * 16 + i + 1)) & 1u) ? p.y : 0.f; }
;       Sx[mt][i] = p.x; Sx[mt][i + 1] = p.y;
;       sum2 += p;
;     }
;   l = l * alpha + (sum2.x + sum2.y);
;   m = mn;
;   return alpha;
; }
.LBB0_770:
	v_cmp_le_i32_e32 vcc, s78, v245
	s_and_saveexec_b64 s[74:75], vcc
	s_cbranch_execz .LBB0_767
	ds_read_b128 v[0:3], v249
	ds_read_b128 v[4:7], v249 offset:32
	ds_read_b128 v[8:11], v249 offset:64
	ds_read_b128 v[12:15], v249 offset:96
	ds_read_b128 v[16:19], v249 offset:4608
	ds_read_b128 v[20:23], v249 offset:4640
	ds_read_b128 v[24:27], v249 offset:4672
	ds_read_b128 v[28:31], v249 offset:4704
	s_add_i32 s0, s80, -1
	v_cmp_le_i32_e32 vcc, s0, v244
	s_waitcnt lgkmcnt(7)
	v_mfma_f32_32x32x16_bf16 v[128:143], v[0:3], v[144:147], 0
	s_waitcnt lgkmcnt(6)
	v_mfma_f32_32x32x16_bf16 v[128:143], v[4:7], v[148:151], v[128:143]
	s_waitcnt lgkmcnt(5)
	v_mfma_f32_32x32x16_bf16 v[128:143], v[8:11], v[152:155], v[128:143]
	s_waitcnt lgkmcnt(4)
	v_mfma_f32_32x32x16_bf16 v[128:143], v[12:15], v[156:159], v[128:143]
	s_waitcnt lgkmcnt(3)
	v_mfma_f32_32x32x16_bf16 v[112:127], v[16:19], v[144:147], 0
	s_waitcnt lgkmcnt(2)
	v_mfma_f32_32x32x16_bf16 v[112:127], v[20:23], v[148:151], v[112:127]
	s_waitcnt lgkmcnt(1)
	v_mfma_f32_32x32x16_bf16 v[112:127], v[24:27], v[152:155], v[112:127]
	s_waitcnt lgkmcnt(0)
	v_mfma_f32_32x32x16_bf16 v[112:127], v[28:31], v[156:159], v[112:127]
	s_and_saveexec_b64 s[0:1], vcc
	s_xor_b64 s[0:1], exec, s[0:1]
	s_cbranch_execz .LBB0_773
	v_max3_f32 v0, v128, s92, v129
	v_max3_f32 v0, v0, v130, v131
	v_max3_f32 v0, v0, v132, v133
	v_max3_f32 v0, v0, v134, v135
	v_max3_f32 v0, v0, v136, v137
	v_max3_f32 v0, v0, v138, v139
	v_max3_f32 v0, v0, v140, v141
	v_max3_f32 v0, v0, v142, v143
	s_nop 0
	v_max3_f32 v0, v0, v112, v113
	v_max3_f32 v0, v0, v114, v115
	v_max3_f32 v0, v0, v116, v117
	v_max3_f32 v0, v0, v118, v119
	v_max3_f32 v0, v0, v120, v121
	v_max3_f32 v0, v0, v122, v123
	v_max3_f32 v0, v0, v124, v125
	v_max3_f32 v0, v0, v126, v127
	ds_bpermute_b32 v1, v200, v0
	s_mov_b32 s2, 0x3fb8aa3b
	s_waitcnt lgkmcnt(0)
	v_max3_f32 v36, v198, v0, v1
	v_mul_f32_e32 v30, 0x3fb8aa3b, v36
	v_pk_fma_f32 v[0:1], v[128:129], s[2:3], v[30:31] op_sel_hi:[1,0,0] neg_lo:[0,0,1] neg_hi:[0,0,1]
	v_pk_fma_f32 v[2:3], v[130:131], s[2:3], v[30:31] op_sel_hi:[1,0,0] neg_lo:[0,0,1] neg_hi:[0,0,1]
	v_exp_f32_e32 v0, v0
	v_exp_f32_e32 v1, v1
	v_exp_f32_e32 v2, v2
	v_exp_f32_e32 v3, v3
	v_sub_f32_e32 v32, v198, v36
	v_pk_add_f32 v[4:5], v[0:1], 0 op_sel_hi:[1,0]
	v_mul_f32_e32 v32, 0x3fb8aa3b, v32
	v_pk_add_f32 v[6:7], v[2:3], v[4:5]
	v_pk_fma_f32 v[4:5], v[132:133], s[2:3], v[30:31] op_sel_hi:[1,0,0] neg_lo:[0,0,1] neg_hi:[0,0,1]
	v_exp_f32_e32 v32, v32
	v_exp_f32_e32 v4, v4
	v_exp_f32_e32 v5, v5
	s_nop 0
	v_pk_add_f32 v[8:9], v[4:5], v[6:7]
	v_pk_fma_f32 v[6:7], v[134:135], s[2:3], v[30:31] op_sel_hi:[1,0,0] neg_lo:[0,0,1] neg_hi:[0,0,1]
	s_nop 0
	v_exp_f32_e32 v6, v6
	v_exp_f32_e32 v7, v7
	s_nop 0
	v_pk_add_f32 v[10:11], v[6:7], v[8:9]
	v_pk_fma_f32 v[8:9], v[136:137], s[2:3], v[30:31] op_sel_hi:[1,0,0] neg_lo:[0,0,1] neg_hi:[0,0,1]
	s_nop 0
	v_exp_f32_e32 v8, v8
	v_exp_f32_e32 v9, v9
	s_nop 0
	v_pk_add_f32 v[12:13], v[8:9], v[10:11]
	v_pk_fma_f32 v[10:11], v[138:139], s[2:3], v[30:31] op_sel_hi:[1,0,0] neg_lo:[0,0,1] neg_hi:[0,0,1]
	s_nop 0
	v_exp_f32_e32 v10, v10
	v_exp_f32_e32 v11, v11
	s_nop 0
	v_pk_add_f32 v[14:15], v[10:11], v[12:13]
	v_pk_fma_f32 v[12:13], v[140:141], s[2:3], v[30:31] op_sel_hi:[1,0,0] neg_lo:[0,0,1] neg_hi:[0,0,1]
	s_nop 0
	v_exp_f32_e32 v12, v12
	v_exp_f32_e32 v13, v13
	s_nop 0
	v_pk_add_f32 v[16:17], v[12:13], v[14:15]
	v_pk_fma_f32 v[14:15], v[142:143], s[2:3], v[30:31] op_sel_hi:[1,0,0] neg_lo:[0,0,1] neg_hi:[0,0,1]
	s_nop 0
	v_exp_f32_e32 v14, v14
	v_exp_f32_e32 v15, v15
	s_nop 0
	v_pk_add_f32 v[18:19], v[14:15], v[16:17]
	v_pk_fma_f32 v[16:17], v[112:113], s[2:3], v[30:31] op_sel_hi:[1,0,0] neg_lo:[0,0,1] neg_hi:[0,0,1]
	s_nop 0
	v_exp_f32_e32 v16, v16
	v_exp_f32_e32 v17, v17
	s_nop 0
	v_pk_add_f32 v[20:21], v[16:17], v[18:19]
	v_pk_fma_f32 v[18:19], v[114:115], s[2:3], v[30:31] op_sel_hi:[1,0,0] neg_lo:[0,0,1] neg_hi:[0,0,1]
	s_nop 0
	v_exp_f32_e32 v18, v18
	v_exp_f32_e32 v19, v19
	s_nop 0
	v_pk_add_f32 v[22:23], v[18:19], v[20:21]
	v_pk_fma_f32 v[20:21], v[116:117], s[2:3], v[30:31] op_sel_hi:[1,0,0] neg_lo:[0,0,1] neg_hi:[0,0,1]
	s_nop 0
	v_exp_f32_e32 v20, v20
	v_exp_f32_e32 v21, v21
	s_nop 0
	v_pk_add_f32 v[24:25], v[20:21], v[22:23]
	v_pk_fma_f32 v[22:23], v[118:119], s[2:3], v[30:31] op_sel_hi:[1,0,0] neg_lo:[0,0,1] neg_hi:[0,0,1]
	s_nop 0
	v_exp_f32_e32 v22, v22
	v_exp_f32_e32 v23, v23
	s_nop 0
	v_pk_add_f32 v[26:27], v[22:23], v[24:25]
	v_pk_fma_f32 v[24:25], v[120:121], s[2:3], v[30:31] op_sel_hi:[1,0,0] neg_lo:[0,0,1] neg_hi:[0,0,1]
	s_nop 0
	v_exp_f32_e32 v24, v24
	v_exp_f32_e32 v25, v25
	s_nop 0
	v_pk_add_f32 v[28:29], v[24:25], v[26:27]
	v_pk_fma_f32 v[26:27], v[122:123], s[2:3], v[30:31] op_sel_hi:[1,0,0] neg_lo:[0,0,1] neg_hi:[0,0,1]
	s_nop 0
	v_exp_f32_e32 v26, v26
	v_exp_f32_e32 v27, v27
	s_nop 0
	v_pk_add_f32 v[34:35], v[26:27], v[28:29]
	v_pk_fma_f32 v[28:29], v[124:125], s[2:3], v[30:31] op_sel_hi:[1,0,0] neg_lo:[0,0,1] neg_hi:[0,0,1]
	v_pk_fma_f32 v[30:31], v[126:127], s[2:3], v[30:31] op_sel_hi:[1,0,0] neg_lo:[0,0,1] neg_hi:[0,0,1]
	v_exp_f32_e32 v28, v28
	v_exp_f32_e32 v29, v29
	v_exp_f32_e32 v30, v30
	v_exp_f32_e32 v31, v31
	v_pk_add_f32 v[34:35], v[28:29], v[34:35]
	s_nop 0
	v_pk_add_f32 v[34:35], v[30:31], v[34:35]
	s_nop 0
	v_add_f32_e32 v34, v34, v35
	v_fmac_f32_e32 v34, v185, v32
	v_mov_b32_e32 v185, v34
	v_mov_b32_e32 v198, v36
